# v51 + EpiResid GEMM epilogues: trailing half-workgroup enters the epilogue s_sleep 32 after the leading half so one wave's operand-load stalls overlap the partner wave's VALU work
# speedup vs baseline: 1.0009x; 1.0001x over previous
; #define PG8_BAR __builtin_amdgcn_s_barrier()
; template <class Epi, class Sched, bool ALIGN_EPI = false, bool SP2 = false>
; __device__ __forceinline__ void gemm_phase(PG8_LAS unsigned char* lds, const Gemm g, const Sched& S, const Epi& E, const int wv) {
;     ...
;         if constexpr (ALIGN_EPI) { if (wr == 0) PG8_BAR; }
;         if constexpr (!Epi::AFTER_DRAIN) { E(acc, cur, wr, wc, fr, fq); S.done(cur); }
.LBB0_346:
	s_and_b64 vcc, exec, s[18:19]
	s_cbranch_vccnz .Lepd_11199
	s_sleep 32

; #define PG8_BAR __builtin_amdgcn_s_barrier()
; template <class Epi, class Sched, bool ALIGN_EPI = false, bool SP2 = false>
; __device__ __forceinline__ void gemm_phase(PG8_LAS unsigned char* lds, const Gemm g, const Sched& S, const Epi& E, const int wv) {
;     ...
;         if constexpr (ALIGN_EPI) { if (wr == 0) PG8_BAR; }
;         if constexpr (!Epi::AFTER_DRAIN) { E(acc, cur, wr, wc, fr, fq); S.done(cur); }
.LBB0_399:
	s_and_b64 vcc, exec, s[20:21]
	s_cbranch_vccnz .Lepd_13886
	s_sleep 32

; #define PG8_BAR __builtin_amdgcn_s_barrier()
; template <class Epi, class Sched, bool ALIGN_EPI = false, bool SP2 = false>
; __device__ __forceinline__ void gemm_phase(PG8_LAS unsigned char* lds, const Gemm g, const Sched& S, const Epi& E, const int wv) {
;     ...
;         if constexpr (ALIGN_EPI) { if (wr == 0) PG8_BAR; }
;         if constexpr (!Epi::AFTER_DRAIN) { E(acc, cur, wr, wc, fr, fq); S.done(cur); }
.LBB0_1034:
	s_and_b64 vcc, exec, s[22:23]
	s_cbranch_vccnz .Lepd_37857
	s_sleep 32

; #define PG8_BAR __builtin_amdgcn_s_barrier()
; template <class Epi, class Sched, bool ALIGN_EPI = false, bool SP2 = false>
; __device__ __forceinline__ void gemm_phase(PG8_LAS unsigned char* lds, const Gemm g, const Sched& S, const Epi& E, const int wv) {
;     ...
;         if constexpr (ALIGN_EPI) { if (wr == 0) PG8_BAR; }
;         if constexpr (!Epi::AFTER_DRAIN) { E(acc, cur, wr, wc, fr, fq); S.done(cur); }
.LBB0_1247:
	s_and_b64 vcc, exec, s[12:13]
	s_cbranch_vccnz .Lepd_44581
	s_sleep 32
